# ss[row] loads of the P14 (EpiSwiglu) and P4 (EpiZ) epilogues hoisted to the epilogue top, per-block vmcnt(0) drains removed (on top of v5)
# baseline (speedup 1.0000x reference)
;     __device__ __forceinline__ void operator()(const f32x4 (&acc)[2][2][4][2], const Unit& u, int wr, int wc, int fr, int fq) const {
;         const int row0 = u.pm * BM + wr * 64 + fr;
;         const int kind = (u.pn == gate_pn) ? 2 : (u.pn >= 16 ? 1 : 0);
;         if (kind == 2 && wc != 0) return;
; #pragma unroll
;         for (int ai = 0; ai < 2; ++ai)
; #pragma unroll
;             for (int m = 0; m < 4; ++m) {
;                 const int row = row0 + ai * HALF + m * 16;
;                 const float rs = rsqrtf(ss[row] * (1.f / DM) + EPS);
;                 if (kind == 2) {
;                     float* gp = gates + (size_t)row * 32 + 8 * fq;
;                     *(f32x4*)gp = acc[ai][0][m][0] * rs; *(f32x4*)(gp + 4) = acc[ai][0][m][1] * rs;
;                 } else {
; #pragma unroll
;                     for (int bj = 0; bj < 2; ++bj) {
;                         const f32x4 v0 = acc[ai][bj][m][0] * rs, v1 = acc[ai][bj][m][1] * rs;
;                         u32x4 w; w.x = pk2(v0[0], v0[1]); w.y = pk2(v0[2], v0[3]); w.z = pk2(v1[0], v1[1]); w.w = pk2(v1[2], v1[3]);
;                         bf16_t* dst;
;                         if (kind == 1) { const int chunk = row >> 5, j = row & 31, ucol = (u.pn - 16) * BM + bj * HALF + wc * 32 + 8 * fq, g = ucol >> 4, half = (ucol >> 3) & 1;
;                             dst = ug + ((((size_t)(g * S5NCB + (chunk >> 4)) * 32 + j) * 16 + (chunk & 15)) * 16 + half * 8); }
.LBB0_462:
	s_cmp_eq_u32 s4, 20
	s_cselect_b64 s[8:9], -1, 0
	s_cmp_lg_u32 s4, 20
	s_cselect_b64 s[42:43], -1, 0
	s_and_b64 s[40:41], s[26:27], s[8:9]
	s_and_b64 vcc, exec, s[40:41]
	s_cbranch_vccnz .LBB0_559
	s_lshl_b32 s35, s6, 8
	s_add_i32 s35, s35, s54
	v_or_b32_e32 v152, s35, v141
	v_ashrrev_i32_e32 v153, 31, v152
	v_lshl_add_u64 v[154:155], v[152:153], 2, s[18:19]
	global_load_dword v136, v[154:155], off
	global_load_dword v236, v[154:155], off offset:64
	global_load_dword v237, v[154:155], off offset:128
	global_load_dword v238, v[154:155], off offset:192
	global_load_dword v239, v[154:155], off offset:512
	global_load_dword v240, v[154:155], off offset:576
	global_load_dword v241, v[154:155], off offset:640
	global_load_dword v242, v[154:155], off offset:704
	v_cndmask_b32_e64 v156, 0, 1, s[42:43]
	s_cmp_gt_i32 s4, 15
	v_cmp_ne_u32_e64 s[6:7], 1, v156
	s_cselect_b64 s[78:79], -1, 0
	s_lshl_b32 s40, s4, 8
	s_xor_b64 s[8:9], s[8:9], -1
	s_mov_b64 s[44:45], -1
	s_ashr_i32 s31, s35, 9
	s_and_b64 s[8:9], s[78:79], s[8:9]
	v_add_u32_e32 v171, s40, v163
	s_ashr_i32 s41, s40, 31
	s_andn2_b64 vcc, exec, s[42:43]
	s_waitcnt vmcnt(0)
	v_fmamk_f32 v136, v136, 0x3a000000, v170
	v_mul_f32_e32 v156, 0x4b800000, v136
	v_cmp_gt_f32_e64 s[4:5], s64, v136
	s_nop 1
	v_cndmask_b32_e64 v136, v136, v156, s[4:5]
	v_rsq_f32_e32 v136, v136
	s_nop 0
	v_mul_f32_e32 v156, 0x45800000, v136
	v_cndmask_b32_e64 v156, v136, v156, s[4:5]
	s_cbranch_vccnz .LBB0_473
	s_and_b32 s4, s35, 0x1c0
	v_or_b32_e32 v136, s4, v164
	s_mov_b64 s[4:5], -1
	s_and_b64 vcc, exec, s[8:9]
	s_cbranch_vccz .LBB0_466
	v_lshrrev_b32_e32 v157, 4, v171
	v_mov_b32_e32 v158, s31
	v_mad_u64_u32 v[158:159], s[4:5], v157, 48, v[158:159]
	v_ashrrev_i32_e32 v159, 31, v158
	v_lshlrev_b64 v[158:159], 14, v[158:159]
	v_lshl_add_u64 v[158:159], s[20:21], 0, v[158:159]
	v_lshl_add_u64 v[158:159], v[158:159], 0, v[136:137]
	v_lshlrev_b32_e32 v160, 1, v140
	v_mov_b32_e32 v161, v137
	v_lshl_add_u64 v[160:161], v[158:159], 0, v[160:161]
	s_mov_b64 s[4:5], 0

;     __device__ __forceinline__ void operator()(const f32x4 (&acc)[2][2][4][2], const Unit& u, int wr, int wc, int fr, int fq) const {
;     ...
;         for (int ai = 0; ai < 2; ++ai)
; #pragma unroll
;             for (int m = 0; m < 4; ++m) {
;                 const int row = row0 + ai * HALF + m * 16;
;                 const float rs = rsqrtf(ss[row] * (1.f / DM) + EPS);
;                 if (kind == 2) {
;                     float* gp = gates + (size_t)row * 32 + 8 * fq;
;                     *(f32x4*)gp = acc[ai][0][m][0] * rs; *(f32x4*)(gp + 4) = acc[ai][0][m][1] * rs;
;                 } else {
; #pragma unroll
;                     for (int bj = 0; bj < 2; ++bj) {
;                         const f32x4 v0 = acc[ai][bj][m][0] * rs, v1 = acc[ai][bj][m][1] * rs;
;                         u32x4 w; w.x = pk2(v0[0], v0[1]); w.y = pk2(v0[2], v0[3]); w.z = pk2(v1[0], v1[1]); w.w = pk2(v1[2], v1[3]);
;                         bf16_t* dst;
;                         if (kind == 1) { const int chunk = row >> 5, j = row & 31, ucol = (u.pn - 16) * BM + bj * HALF + wc * 32 + 8 * fq, g = ucol >> 4, half = (ucol >> 3) & 1;
;                             dst = ug + ((((size_t)(g * S5NCB + (chunk >> 4)) * 32 + j) * 16 + (chunk & 15)) * 16 + half * 8); }
;                         else dst = O + (size_t)row * ldc + u.pn * BM + bj * HALF + wc * 32 + 8 * fq;
;                         *(u32x4*)dst = w;
.LBB0_475:
	s_nop 1
	v_or_b32_e32 v112, 16, v152
	v_ashrrev_i32_e32 v113, 31, v112
	v_lshl_add_u64 v[114:115], v[112:113], 2, s[18:19]
	s_nop 1
	v_mov_b32_e32 v114, v236
	s_mov_b64 s[42:43], -1
	s_and_b64 vcc, exec, s[6:7]
	s_nop 0
	v_fmamk_f32 v114, v114, 0x3a000000, v170
	v_mul_f32_e32 v115, 0x4b800000, v114
	v_cmp_gt_f32_e64 s[4:5], s64, v114
	s_nop 1
	v_cndmask_b32_e64 v114, v114, v115, s[4:5]
	v_rsq_f32_e32 v114, v114
	v_cndmask_b32_e64 v115, 0, 1, s[8:9]
	v_mul_f32_e32 v116, 0x45800000, v114
	v_cndmask_b32_e64 v114, v114, v116, s[4:5]
	v_cmp_ne_u32_e64 s[4:5], 1, v115
	s_cbranch_vccnz .LBB0_485
	v_lshlrev_b32_e32 v115, 9, v112
	v_and_b32_e32 v115, 0x3e00, v115
	s_and_b32 s8, s35, 0x1c0
	v_or_b32_e32 v136, s8, v115
	s_and_b64 vcc, exec, s[4:5]
	s_mov_b64 s[8:9], -1
	s_cbranch_vccnz .LBB0_478
	v_lshrrev_b32_e32 v115, 4, v171
	v_mov_b32_e32 v116, s31
	v_mad_u64_u32 v[116:117], s[8:9], v115, 48, v[116:117]
	v_ashrrev_i32_e32 v117, 31, v116
	v_lshlrev_b64 v[116:117], 14, v[116:117]
	v_lshl_add_u64 v[116:117], s[20:21], 0, v[116:117]
	v_lshl_add_u64 v[116:117], v[116:117], 0, v[136:137]
	v_lshlrev_b32_e32 v118, 1, v140
	v_mov_b32_e32 v119, v137
	v_lshl_add_u64 v[118:119], v[116:117], 0, v[118:119]
	s_mov_b64 s[8:9], 0

;     __device__ __forceinline__ void operator()(const f32x4 (&acc)[2][2][4][2], const Unit& u, int wr, int wc, int fr, int fq) const {
;     ...
;         for (int ai = 0; ai < 2; ++ai)
; #pragma unroll
;             for (int m = 0; m < 4; ++m) {
;                 const int row = row0 + ai * HALF + m * 16;
;                 const float rs = rsqrtf(ss[row] * (1.f / DM) + EPS);
;                 if (kind == 2) {
;                     float* gp = gates + (size_t)row * 32 + 8 * fq;
;                     *(f32x4*)gp = acc[ai][0][m][0] * rs; *(f32x4*)(gp + 4) = acc[ai][0][m][1] * rs;
;                 } else {
; #pragma unroll
;                     for (int bj = 0; bj < 2; ++bj) {
;                         const f32x4 v0 = acc[ai][bj][m][0] * rs, v1 = acc[ai][bj][m][1] * rs;
;                         u32x4 w; w.x = pk2(v0[0], v0[1]); w.y = pk2(v0[2], v0[3]); w.z = pk2(v1[0], v1[1]); w.w = pk2(v1[2], v1[3]);
;                         bf16_t* dst;
;                         if (kind == 1) { const int chunk = row >> 5, j = row & 31, ucol = (u.pn - 16) * BM + bj * HALF + wc * 32 + 8 * fq, g = ucol >> 4, half = (ucol >> 3) & 1;
;                             dst = ug + ((((size_t)(g * S5NCB + (chunk >> 4)) * 32 + j) * 16 + (chunk & 15)) * 16 + half * 8); }
;                         else dst = O + (size_t)row * ldc + u.pn * BM + bj * HALF + wc * 32 + 8 * fq;
;                         *(u32x4*)dst = w;
.LBB0_487:
	s_nop 1
	v_or_b32_e32 v96, 32, v152
	v_ashrrev_i32_e32 v97, 31, v96
	v_lshl_add_u64 v[98:99], v[96:97], 2, s[18:19]
	s_nop 1
	v_mov_b32_e32 v98, v237
	s_and_b64 vcc, exec, s[6:7]
	s_nop 0
	v_fmamk_f32 v98, v98, 0x3a000000, v170
	v_mul_f32_e32 v99, 0x4b800000, v98
	v_cmp_gt_f32_e64 s[8:9], s64, v98
	s_nop 1
	v_cndmask_b32_e64 v98, v98, v99, s[8:9]
	v_rsq_f32_e32 v98, v98
	s_nop 0
	v_mul_f32_e32 v99, 0x45800000, v98
	v_cndmask_b32_e64 v98, v98, v99, s[8:9]
	s_mov_b64 s[8:9], -1
	s_cbranch_vccnz .LBB0_497
	v_and_or_b32 v136, v96, s69, v164
	s_and_b64 vcc, exec, s[4:5]
	s_cbranch_vccnz .LBB0_490
	v_lshrrev_b32_e32 v99, 4, v171
	v_mov_b32_e32 v100, s31
	v_mad_u64_u32 v[100:101], s[8:9], v99, 48, v[100:101]
	v_ashrrev_i32_e32 v101, 31, v100
	v_lshlrev_b64 v[100:101], 14, v[100:101]
	v_lshl_add_u64 v[100:101], s[20:21], 0, v[100:101]
	v_lshl_add_u64 v[100:101], v[100:101], 0, v[136:137]
	v_lshlrev_b32_e32 v102, 1, v140
	v_mov_b32_e32 v103, v137
	v_lshl_add_u64 v[102:103], v[100:101], 0, v[102:103]
	s_mov_b64 s[8:9], 0

;     __device__ __forceinline__ void operator()(const f32x4 (&acc)[2][2][4][2], const Unit& u, int wr, int wc, int fr, int fq) const {
;     ...
;         for (int ai = 0; ai < 2; ++ai)
; #pragma unroll
;             for (int m = 0; m < 4; ++m) {
;                 const int row = row0 + ai * HALF + m * 16;
;                 const float rs = rsqrtf(ss[row] * (1.f / DM) + EPS);
;                 if (kind == 2) {
;                     float* gp = gates + (size_t)row * 32 + 8 * fq;
;                     *(f32x4*)gp = acc[ai][0][m][0] * rs; *(f32x4*)(gp + 4) = acc[ai][0][m][1] * rs;
;                 } else {
; #pragma unroll
;                     for (int bj = 0; bj < 2; ++bj) {
;                         const f32x4 v0 = acc[ai][bj][m][0] * rs, v1 = acc[ai][bj][m][1] * rs;
;                         u32x4 w; w.x = pk2(v0[0], v0[1]); w.y = pk2(v0[2], v0[3]); w.z = pk2(v1[0], v1[1]); w.w = pk2(v1[2], v1[3]);
;                         bf16_t* dst;
;                         if (kind == 1) { const int chunk = row >> 5, j = row & 31, ucol = (u.pn - 16) * BM + bj * HALF + wc * 32 + 8 * fq, g = ucol >> 4, half = (ucol >> 3) & 1;
;                             dst = ug + ((((size_t)(g * S5NCB + (chunk >> 4)) * 32 + j) * 16 + (chunk & 15)) * 16 + half * 8); }
;                         else dst = O + (size_t)row * ldc + u.pn * BM + bj * HALF + wc * 32 + 8 * fq;
;                         *(u32x4*)dst = w;
.LBB0_499:
	s_nop 1
	v_or_b32_e32 v80, 48, v152
	v_ashrrev_i32_e32 v81, 31, v80
	v_lshl_add_u64 v[82:83], v[80:81], 2, s[18:19]
	s_nop 1
	v_mov_b32_e32 v82, v238
	s_and_b64 vcc, exec, s[6:7]
	s_nop 0
	v_fmamk_f32 v82, v82, 0x3a000000, v170
	v_mul_f32_e32 v83, 0x4b800000, v82
	v_cmp_gt_f32_e64 s[8:9], s64, v82
	s_nop 1
	v_cndmask_b32_e64 v82, v82, v83, s[8:9]
	v_rsq_f32_e32 v82, v82
	s_nop 0
	v_mul_f32_e32 v83, 0x45800000, v82
	v_cndmask_b32_e64 v82, v82, v83, s[8:9]
	s_mov_b64 s[8:9], -1
	s_cbranch_vccnz .LBB0_509
	v_lshlrev_b32_e32 v83, 9, v80
	v_and_b32_e32 v84, 0x1e0, v80
	v_and_or_b32 v136, v83, s68, v84
	s_and_b64 vcc, exec, s[4:5]
	s_cbranch_vccnz .LBB0_502
	v_lshrrev_b32_e32 v83, 4, v171
	v_mov_b32_e32 v84, s31
	v_mad_u64_u32 v[84:85], s[8:9], v83, 48, v[84:85]
	v_ashrrev_i32_e32 v85, 31, v84
	v_lshlrev_b64 v[84:85], 14, v[84:85]
	v_lshl_add_u64 v[84:85], s[20:21], 0, v[84:85]
	v_lshl_add_u64 v[84:85], v[84:85], 0, v[136:137]
	v_lshlrev_b32_e32 v86, 1, v140
	v_mov_b32_e32 v87, v137
	v_lshl_add_u64 v[86:87], v[84:85], 0, v[86:87]
	s_mov_b64 s[8:9], 0

;     __device__ __forceinline__ void operator()(const f32x4 (&acc)[2][2][4][2], const Unit& u, int wr, int wc, int fr, int fq) const {
;     ...
;         for (int ai = 0; ai < 2; ++ai)
; #pragma unroll
;             for (int m = 0; m < 4; ++m) {
;                 const int row = row0 + ai * HALF + m * 16;
;                 const float rs = rsqrtf(ss[row] * (1.f / DM) + EPS);
;                 if (kind == 2) {
;                     float* gp = gates + (size_t)row * 32 + 8 * fq;
;                     *(f32x4*)gp = acc[ai][0][m][0] * rs; *(f32x4*)(gp + 4) = acc[ai][0][m][1] * rs;
;                 } else {
; #pragma unroll
;                     for (int bj = 0; bj < 2; ++bj) {
;                         const f32x4 v0 = acc[ai][bj][m][0] * rs, v1 = acc[ai][bj][m][1] * rs;
;                         u32x4 w; w.x = pk2(v0[0], v0[1]); w.y = pk2(v0[2], v0[3]); w.z = pk2(v1[0], v1[1]); w.w = pk2(v1[2], v1[3]);
;                         bf16_t* dst;
;                         if (kind == 1) { const int chunk = row >> 5, j = row & 31, ucol = (u.pn - 16) * BM + bj * HALF + wc * 32 + 8 * fq, g = ucol >> 4, half = (ucol >> 3) & 1;
;                             dst = ug + ((((size_t)(g * S5NCB + (chunk >> 4)) * 32 + j) * 16 + (chunk & 15)) * 16 + half * 8); }
;                         else dst = O + (size_t)row * ldc + u.pn * BM + bj * HALF + wc * 32 + 8 * fq;
;                         *(u32x4*)dst = w;
.LBB0_511:
	s_nop 1
	v_mov_b32_e32 v64, v239
	v_add_u32_e32 v68, 0x80, v152
	s_and_b64 vcc, exec, s[6:7]
	v_ashrrev_i32_e32 v69, 31, v68
	s_nop 0
	v_fmamk_f32 v64, v64, 0x3a000000, v170
	v_mul_f32_e32 v65, 0x4b800000, v64
	v_cmp_gt_f32_e64 s[8:9], s64, v64
	s_nop 1
	v_cndmask_b32_e64 v64, v64, v65, s[8:9]
	v_rsq_f32_e32 v65, v64
	v_ashrrev_i32_e32 v64, 9, v68
	v_mul_f32_e32 v66, 0x45800000, v65
	v_cndmask_b32_e64 v66, v65, v66, s[8:9]
	s_mov_b64 s[8:9], -1
	s_cbranch_vccnz .LBB0_521
	v_and_or_b32 v136, v68, s65, v164
	s_and_b64 vcc, exec, s[4:5]
	s_cbranch_vccnz .LBB0_514
	v_lshrrev_b32_e32 v65, 4, v171
	v_mad_u64_u32 v[70:71], s[8:9], v65, 48, v[64:65]
	v_ashrrev_i32_e32 v71, 31, v70
	v_lshlrev_b64 v[70:71], 14, v[70:71]
	v_lshl_add_u64 v[70:71], s[20:21], 0, v[70:71]
	v_lshl_add_u64 v[70:71], v[70:71], 0, v[136:137]
	v_lshlrev_b32_e32 v72, 1, v140
	v_mov_b32_e32 v73, v137
	v_lshl_add_u64 v[72:73], v[70:71], 0, v[72:73]
	s_mov_b64 s[8:9], 0

;     __device__ __forceinline__ void operator()(const f32x4 (&acc)[2][2][4][2], const Unit& u, int wr, int wc, int fr, int fq) const {
;     ...
;         for (int ai = 0; ai < 2; ++ai)
; #pragma unroll
;             for (int m = 0; m < 4; ++m) {
;                 const int row = row0 + ai * HALF + m * 16;
;                 const float rs = rsqrtf(ss[row] * (1.f / DM) + EPS);
;                 if (kind == 2) {
;                     float* gp = gates + (size_t)row * 32 + 8 * fq;
;                     *(f32x4*)gp = acc[ai][0][m][0] * rs; *(f32x4*)(gp + 4) = acc[ai][0][m][1] * rs;
;                 } else {
; #pragma unroll
;                     for (int bj = 0; bj < 2; ++bj) {
;                         const f32x4 v0 = acc[ai][bj][m][0] * rs, v1 = acc[ai][bj][m][1] * rs;
;                         u32x4 w; w.x = pk2(v0[0], v0[1]); w.y = pk2(v0[2], v0[3]); w.z = pk2(v1[0], v1[1]); w.w = pk2(v1[2], v1[3]);
;                         bf16_t* dst;
;                         if (kind == 1) { const int chunk = row >> 5, j = row & 31, ucol = (u.pn - 16) * BM + bj * HALF + wc * 32 + 8 * fq, g = ucol >> 4, half = (ucol >> 3) & 1;
;                             dst = ug + ((((size_t)(g * S5NCB + (chunk >> 4)) * 32 + j) * 16 + (chunk & 15)) * 16 + half * 8); }
;                         else dst = O + (size_t)row * ldc + u.pn * BM + bj * HALF + wc * 32 + 8 * fq;
;                         *(u32x4*)dst = w;
.LBB0_523:
	s_nop 1
	v_mov_b32_e32 v48, v240
	s_nop 0
	v_add_u32_e32 v50, 0x90, v152
	s_and_b64 vcc, exec, s[6:7]
	v_ashrrev_i32_e32 v51, 31, v50
	s_nop 0
	v_fmamk_f32 v48, v48, 0x3a000000, v170
	v_mul_f32_e32 v49, 0x4b800000, v48
	v_cmp_gt_f32_e64 s[8:9], s64, v48
	s_nop 1
	v_cndmask_b32_e64 v48, v48, v49, s[8:9]
	v_rsq_f32_e32 v48, v48
	s_nop 0
	v_mul_f32_e32 v49, 0x45800000, v48
	v_cndmask_b32_e64 v48, v48, v49, s[8:9]
	s_mov_b64 s[8:9], -1
	s_cbranch_vccnz .LBB0_533
	v_lshlrev_b32_e32 v49, 9, v50
	v_and_b32_e32 v52, 0x1c0, v50
	v_and_or_b32 v136, v49, s68, v52
	s_and_b64 vcc, exec, s[4:5]
	s_cbranch_vccnz .LBB0_526
	v_lshrrev_b32_e32 v49, 4, v171
	v_mad_u64_u32 v[52:53], s[8:9], v49, 48, v[64:65]
	v_ashrrev_i32_e32 v53, 31, v52
	v_lshlrev_b64 v[52:53], 14, v[52:53]
	v_lshl_add_u64 v[52:53], s[20:21], 0, v[52:53]
	v_lshl_add_u64 v[52:53], v[52:53], 0, v[136:137]
	v_lshlrev_b32_e32 v54, 1, v140
	v_mov_b32_e32 v55, v137
	v_lshl_add_u64 v[54:55], v[52:53], 0, v[54:55]
	s_mov_b64 s[8:9], 0

;     __device__ __forceinline__ void operator()(const f32x4 (&acc)[2][2][4][2], const Unit& u, int wr, int wc, int fr, int fq) const {
;     ...
;         for (int ai = 0; ai < 2; ++ai)
; #pragma unroll
;             for (int m = 0; m < 4; ++m) {
;                 const int row = row0 + ai * HALF + m * 16;
;                 const float rs = rsqrtf(ss[row] * (1.f / DM) + EPS);
;                 if (kind == 2) {
;                     float* gp = gates + (size_t)row * 32 + 8 * fq;
;                     *(f32x4*)gp = acc[ai][0][m][0] * rs; *(f32x4*)(gp + 4) = acc[ai][0][m][1] * rs;
;                 } else {
; #pragma unroll
;                     for (int bj = 0; bj < 2; ++bj) {
;                         const f32x4 v0 = acc[ai][bj][m][0] * rs, v1 = acc[ai][bj][m][1] * rs;
;                         u32x4 w; w.x = pk2(v0[0], v0[1]); w.y = pk2(v0[2], v0[3]); w.z = pk2(v1[0], v1[1]); w.w = pk2(v1[2], v1[3]);
;                         bf16_t* dst;
;                         if (kind == 1) { const int chunk = row >> 5, j = row & 31, ucol = (u.pn - 16) * BM + bj * HALF + wc * 32 + 8 * fq, g = ucol >> 4, half = (ucol >> 3) & 1;
;                             dst = ug + ((((size_t)(g * S5NCB + (chunk >> 4)) * 32 + j) * 16 + (chunk & 15)) * 16 + half * 8); }
;                         else dst = O + (size_t)row * ldc + u.pn * BM + bj * HALF + wc * 32 + 8 * fq;
;                         *(u32x4*)dst = w;
.LBB0_535:
	s_nop 1
	v_mov_b32_e32 v32, v241
	s_nop 0
	v_add_u32_e32 v34, 0xa0, v152
	s_and_b64 vcc, exec, s[6:7]
	v_ashrrev_i32_e32 v35, 31, v34
	s_nop 0
	v_fmamk_f32 v32, v32, 0x3a000000, v170
	v_mul_f32_e32 v33, 0x4b800000, v32
	v_cmp_gt_f32_e64 s[8:9], s64, v32
	s_nop 1
	v_cndmask_b32_e64 v32, v32, v33, s[8:9]
	v_rsq_f32_e32 v32, v32
	s_nop 0
	v_mul_f32_e32 v33, 0x45800000, v32
	v_cndmask_b32_e64 v32, v32, v33, s[8:9]
	s_mov_b64 s[8:9], -1
	s_cbranch_vccnz .LBB0_545
	v_and_or_b32 v136, v34, s69, v164
	s_and_b64 vcc, exec, s[4:5]
	s_cbranch_vccnz .LBB0_538
	v_lshrrev_b32_e32 v33, 4, v171
	v_mad_u64_u32 v[36:37], s[8:9], v33, 48, v[64:65]
	v_ashrrev_i32_e32 v37, 31, v36
	v_lshlrev_b64 v[36:37], 14, v[36:37]
	v_lshl_add_u64 v[36:37], s[20:21], 0, v[36:37]
	v_lshl_add_u64 v[36:37], v[36:37], 0, v[136:137]
	v_lshlrev_b32_e32 v38, 1, v140
	v_mov_b32_e32 v39, v137
	v_lshl_add_u64 v[38:39], v[36:37], 0, v[38:39]
	s_mov_b64 s[8:9], 0

;     __device__ __forceinline__ void operator()(const f32x4 (&acc)[2][2][4][2], const Unit& u, int wr, int wc, int fr, int fq) const {
;     ...
;         for (int ai = 0; ai < 2; ++ai)
; #pragma unroll
;             for (int m = 0; m < 4; ++m) {
;                 const int row = row0 + ai * HALF + m * 16;
;                 const float rs = rsqrtf(ss[row] * (1.f / DM) + EPS);
;                 if (kind == 2) {
;                     float* gp = gates + (size_t)row * 32 + 8 * fq;
;                     *(f32x4*)gp = acc[ai][0][m][0] * rs; *(f32x4*)(gp + 4) = acc[ai][0][m][1] * rs;
;                 } else {
; #pragma unroll
;                     for (int bj = 0; bj < 2; ++bj) {
;                         const f32x4 v0 = acc[ai][bj][m][0] * rs, v1 = acc[ai][bj][m][1] * rs;
;                         u32x4 w; w.x = pk2(v0[0], v0[1]); w.y = pk2(v0[2], v0[3]); w.z = pk2(v1[0], v1[1]); w.w = pk2(v1[2], v1[3]);
;                         bf16_t* dst;
;                         if (kind == 1) { const int chunk = row >> 5, j = row & 31, ucol = (u.pn - 16) * BM + bj * HALF + wc * 32 + 8 * fq, g = ucol >> 4, half = (ucol >> 3) & 1;
;                             dst = ug + ((((size_t)(g * S5NCB + (chunk >> 4)) * 32 + j) * 16 + (chunk & 15)) * 16 + half * 8); }
;                         else dst = O + (size_t)row * ldc + u.pn * BM + bj * HALF + wc * 32 + 8 * fq;
;                         *(u32x4*)dst = w;
.LBB0_547:
	s_nop 1
	v_mov_b32_e32 v16, v242
	s_nop 0
	v_add_u32_e32 v18, 0xb0, v152
	s_and_b64 vcc, exec, s[6:7]
	v_ashrrev_i32_e32 v19, 31, v18
	s_mov_b64 s[6:7], -1
	s_nop 0
	v_fmamk_f32 v16, v16, 0x3a000000, v170
	v_mul_f32_e32 v17, 0x4b800000, v16
	v_cmp_gt_f32_e64 s[8:9], s64, v16
	s_nop 1
	v_cndmask_b32_e64 v16, v16, v17, s[8:9]
	v_rsq_f32_e32 v16, v16
	s_nop 0
	v_mul_f32_e32 v17, 0x45800000, v16
	v_cndmask_b32_e64 v16, v16, v17, s[8:9]
	s_cbranch_vccnz .LBB0_557
	v_lshlrev_b32_e32 v17, 9, v18
	v_and_b32_e32 v20, 0x1e0, v18
	v_and_or_b32 v136, v17, s68, v20
	s_and_b64 vcc, exec, s[4:5]
	v_lshrrev_b32_e32 v17, 4, v171
	v_lshlrev_b32_e32 v20, 1, v140
	s_cbranch_vccnz .LBB0_550
	v_mad_u64_u32 v[22:23], s[6:7], v17, 48, v[64:65]
	v_ashrrev_i32_e32 v23, 31, v22
	v_lshlrev_b64 v[22:23], 14, v[22:23]
	v_lshl_add_u64 v[22:23], s[20:21], 0, v[22:23]
	v_lshl_add_u64 v[22:23], v[22:23], 0, v[136:137]
	v_mov_b32_e32 v21, v137
	v_lshl_add_u64 v[26:27], v[22:23], 0, v[20:21]
	s_mov_b64 s[6:7], 0

; __device__ __forceinline__ float sigmoid_f(float x) { return __builtin_amdgcn_rcpf(1.f + __expf(-x)); }
; __device__ __forceinline__ float silu_f(float x) { return x * sigmoid_f(x); }
;     __device__ __forceinline__ void operator()(const f32x4 (&acc)[2][2][4][2], const Unit& u, int wr, int wc, int fr, int fq) const {
;         const int row0 = u.pm * BM + wr * 64 + fr, col0 = u.pn * HALF + wc * 32 + 8 * fq;
; #pragma unroll
;         for (int ai = 0; ai < 2; ++ai)
; #pragma unroll
;             for (int m = 0; m < 4; ++m) {
;                 bf16_t* rowp = O + (size_t)(row0 + ai * HALF + m * 16) * ldc + col0;
;                 const float rs = ss ? rsqrtf(ss[row0 + ai * HALF + m * 16] * (1.f / DM) + EPS) : 1.f;
;                 const f32x4 g0 = acc[ai][0][m][0] * rs, g1 = acc[ai][0][m][1] * rs, u0 = acc[ai][1][m][0] * rs, u1 = acc[ai][1][m][1] * rs;
;                 float r[8];
; #pragma unroll
;                 for (int i = 0; i < 4; ++i) {
;                     r[i] = glu ? g0[i] * sigmoid_f(u0[i]) : silu_f(g0[i]) * u0[i];
;                     r[4 + i] = glu ? g1[i] * sigmoid_f(u1[i]) : silu_f(g1[i]) * u1[i];
;                 }
;                 u32x4 w; w.x = pk2(r[0], r[1]); w.y = pk2(r[2], r[3]); w.z = pk2(r[4], r[5]); w.w = pk2(r[6], r[7]);
;                 *(u32x4*)rowp = w;
.LBB0_1296:
	v_lshl_add_u32 v144, s4, 8, v153
	v_ashrrev_i32_e32 v145, 31, v144
	v_lshl_add_u64 v[150:151], v[144:145], 2, s[10:11]
	global_load_dword v145, v[150:151], off
	global_load_dword v228, v[150:151], off offset:64
	global_load_dword v229, v[150:151], off offset:128
	global_load_dword v230, v[150:151], off offset:192
	global_load_dword v231, v[150:151], off offset:512
	global_load_dword v232, v[150:151], off offset:576
	global_load_dword v233, v[150:151], off offset:640
	global_load_dword v234, v[150:151], off offset:704
	v_or_b32_e32 v162, 16, v144
	v_lshl_or_b32 v148, s5, 7, v155
	v_mov_b64_e32 v[146:147], s[8:9]
	v_ashrrev_i32_e32 v149, 31, v148
	v_mad_i64_i32 v[160:161], s[4:5], v144, s49, v[146:147]
	v_lshlrev_b64 v[148:149], 1, v[148:149]
	v_lshl_add_u64 v[160:161], v[160:161], 0, v[148:149]
	s_waitcnt vmcnt(0)
	v_fmamk_f32 v145, v145, 0x3a000000, v159
	v_mul_f32_e32 v163, 0x4b800000, v145
	v_cmp_gt_f32_e32 vcc, s50, v145
	s_nop 1
	v_cndmask_b32_e32 v145, v145, v163, vcc
	v_rsq_f32_e32 v145, v145
	v_ashrrev_i32_e32 v163, 31, v162
	v_lshl_add_u64 v[164:165], v[162:163], 2, s[10:11]
	v_mul_f32_e32 v163, 0x45800000, v145
	v_cndmask_b32_e32 v168, v145, v163, vcc
	v_pk_mul_f32 v[126:127], v[126:127], v[168:169] op_sel_hi:[1,0]
	v_pk_mul_f32 v[124:125], v[124:125], v[168:169] op_sel_hi:[1,0]
	v_pk_mul_f32 v[122:123], v[122:123], v[168:169] op_sel_hi:[1,0]
	v_pk_mul_f32 v[120:121], v[120:121], v[168:169] op_sel_hi:[1,0]
	v_pk_mul_f32 v[118:119], v[118:119], v[168:169] op_sel_hi:[1,0]
	v_pk_mul_f32 v[116:117], v[116:117], v[168:169] op_sel_hi:[1,0]
	v_pk_mul_f32 v[114:115], v[114:115], v[168:169] op_sel_hi:[1,0]
	v_pk_mul_f32 v[112:113], v[112:113], v[168:169] op_sel_hi:[1,0]
	v_mul_f32_e32 v145, 0xbfb8aa3b, v124
	v_mul_f32_e32 v163, 0xbfb8aa3b, v120
	v_mul_f32_e32 v168, 0xbfb8aa3b, v125
	v_mul_f32_e32 v169, 0xbfb8aa3b, v121
	v_mul_f32_e32 v170, 0xbfb8aa3b, v126
	v_mul_f32_e32 v171, 0xbfb8aa3b, v122
	v_mul_f32_e32 v172, 0xbfb8aa3b, v127
	v_mul_f32_e32 v173, 0xbfb8aa3b, v123
	v_exp_f32_e32 v145, v145
	v_exp_f32_e32 v163, v163
	v_exp_f32_e32 v168, v168
	v_exp_f32_e32 v169, v169
	v_exp_f32_e32 v170, v170
	v_exp_f32_e32 v171, v171
	v_exp_f32_e32 v172, v172
	v_exp_f32_e32 v173, v173
	v_add_f32_e32 v145, 1.0, v145
	v_add_f32_e32 v163, 1.0, v163
	v_add_f32_e32 v168, 1.0, v168
	v_add_f32_e32 v169, 1.0, v169
	v_add_f32_e32 v170, 1.0, v170
	v_add_f32_e32 v171, 1.0, v171
	v_add_f32_e32 v172, 1.0, v172
	v_add_f32_e32 v173, 1.0, v173
	v_rcp_f32_e32 v145, v145
	v_rcp_f32_e32 v163, v163
	v_rcp_f32_e32 v168, v168
	v_rcp_f32_e32 v169, v169
	v_rcp_f32_e32 v170, v170
	v_rcp_f32_e32 v171, v171
	v_rcp_f32_e32 v172, v172
	v_rcp_f32_e32 v173, v173
	v_mul_f32_e32 v124, v124, v145
	v_mul_f32_e32 v120, v120, v163
	v_mul_f32_e32 v125, v125, v168
	v_mul_f32_e32 v121, v121, v169
	v_mul_f32_e32 v126, v126, v170
	v_mul_f32_e32 v122, v122, v171
	v_mul_f32_e32 v127, v127, v172
	v_mul_f32_e32 v123, v123, v173
	v_mul_f32_e32 v116, v116, v124
	v_mul_f32_e32 v112, v112, v120
	v_mul_f32_e32 v117, v117, v125
	v_mul_f32_e32 v113, v113, v121
	v_mul_f32_e32 v118, v118, v126
	v_mul_f32_e32 v114, v114, v122
	v_mul_f32_e32 v119, v119, v127
	v_mul_f32_e32 v115, v115, v123
	v_add_u32_e32 v116, 0x8000, v116
	v_add_u32_e32 v117, 0x8000, v117
	v_add_u32_e32 v118, 0x8000, v118
	v_add_u32_e32 v119, 0x8000, v119
	v_add_u32_e32 v120, 0x8000, v112
	v_add_u32_e32 v121, 0x8000, v113
	v_add_u32_e32 v122, 0x8000, v114
	v_add_u32_e32 v115, 0x8000, v115
	v_perm_b32 v112, v117, v116, s51
	v_perm_b32 v113, v119, v118, s51
	v_perm_b32 v114, v121, v120, s51
	v_perm_b32 v115, v115, v122, s51
	global_store_dwordx4 v[160:161], v[112:115], off
	s_nop 1
	v_mov_b32_e32 v113, v228
	s_nop 0
	v_or_b32_e32 v112, 32, v144
	v_mad_i64_i32 v[114:115], s[4:5], v162, s49, v[146:147]
	v_lshl_add_u64 v[114:115], v[114:115], 0, v[148:149]
	s_nop 0
	v_fmamk_f32 v113, v113, 0x3a000000, v159
	v_mul_f32_e32 v116, 0x4b800000, v113
	v_cmp_gt_f32_e32 vcc, s50, v113
	s_nop 1
	v_cndmask_b32_e32 v113, v113, v116, vcc
	v_rsq_f32_e32 v118, v113
	v_ashrrev_i32_e32 v113, 31, v112
	v_lshl_add_u64 v[116:117], v[112:113], 2, s[10:11]
	v_mul_f32_e32 v113, 0x45800000, v118
	v_cndmask_b32_e32 v118, v118, v113, vcc
	v_pk_mul_f32 v[110:111], v[110:111], v[118:119] op_sel_hi:[1,0]
	v_pk_mul_f32 v[108:109], v[108:109], v[118:119] op_sel_hi:[1,0]
	v_pk_mul_f32 v[106:107], v[106:107], v[118:119] op_sel_hi:[1,0]
	v_pk_mul_f32 v[104:105], v[104:105], v[118:119] op_sel_hi:[1,0]
	v_pk_mul_f32 v[102:103], v[102:103], v[118:119] op_sel_hi:[1,0]
	v_pk_mul_f32 v[100:101], v[100:101], v[118:119] op_sel_hi:[1,0]
	v_pk_mul_f32 v[98:99], v[98:99], v[118:119] op_sel_hi:[1,0]
	v_pk_mul_f32 v[96:97], v[96:97], v[118:119] op_sel_hi:[1,0]
	v_mul_f32_e32 v113, 0xbfb8aa3b, v108
	v_mul_f32_e32 v118, 0xbfb8aa3b, v104
	v_mul_f32_e32 v119, 0xbfb8aa3b, v109
	v_mul_f32_e32 v120, 0xbfb8aa3b, v105
	v_mul_f32_e32 v121, 0xbfb8aa3b, v110
	v_mul_f32_e32 v122, 0xbfb8aa3b, v106
	v_mul_f32_e32 v123, 0xbfb8aa3b, v111
	v_mul_f32_e32 v124, 0xbfb8aa3b, v107
	v_exp_f32_e32 v113, v113
	v_exp_f32_e32 v118, v118
	v_exp_f32_e32 v119, v119
	v_exp_f32_e32 v120, v120
	v_exp_f32_e32 v121, v121
	v_exp_f32_e32 v122, v122
	v_exp_f32_e32 v123, v123
	v_exp_f32_e32 v124, v124
	v_add_f32_e32 v113, 1.0, v113
	v_add_f32_e32 v118, 1.0, v118
	v_add_f32_e32 v119, 1.0, v119
	v_add_f32_e32 v120, 1.0, v120
	v_add_f32_e32 v121, 1.0, v121
	v_add_f32_e32 v122, 1.0, v122
	v_add_f32_e32 v123, 1.0, v123
	v_add_f32_e32 v124, 1.0, v124
	v_rcp_f32_e32 v113, v113
	v_rcp_f32_e32 v118, v118
	v_rcp_f32_e32 v119, v119
	v_rcp_f32_e32 v120, v120
	v_rcp_f32_e32 v121, v121
	v_rcp_f32_e32 v122, v122
	v_rcp_f32_e32 v123, v123
; __device__ __forceinline__ float sigmoid_f(float x) { return __builtin_amdgcn_rcpf(1.f + __expf(-x)); }
; __device__ __forceinline__ float silu_f(float x) { return x * sigmoid_f(x); }
;     __device__ __forceinline__ void operator()(const f32x4 (&acc)[2][2][4][2], const Unit& u, int wr, int wc, int fr, int fq) const {
;         const int row0 = u.pm * BM + wr * 64 + fr, col0 = u.pn * HALF + wc * 32 + 8 * fq;
; #pragma unroll
;         for (int ai = 0; ai < 2; ++ai)
; #pragma unroll
;             for (int m = 0; m < 4; ++m) {
;                 bf16_t* rowp = O + (size_t)(row0 + ai * HALF + m * 16) * ldc + col0;
;                 const float rs = ss ? rsqrtf(ss[row0 + ai * HALF + m * 16] * (1.f / DM) + EPS) : 1.f;
;                 const f32x4 g0 = acc[ai][0][m][0] * rs, g1 = acc[ai][0][m][1] * rs, u0 = acc[ai][1][m][0] * rs, u1 = acc[ai][1][m][1] * rs;
;                 float r[8];
; #pragma unroll
;                 for (int i = 0; i < 4; ++i) {
;                     r[i] = glu ? g0[i] * sigmoid_f(u0[i]) : silu_f(g0[i]) * u0[i];
;                     r[4 + i] = glu ? g1[i] * sigmoid_f(u1[i]) : silu_f(g1[i]) * u1[i];
;                 }
;                 u32x4 w; w.x = pk2(r[0], r[1]); w.y = pk2(r[2], r[3]); w.z = pk2(r[4], r[5]); w.w = pk2(r[6], r[7]);
;                 *(u32x4*)rowp = w;
	v_rcp_f32_e32 v124, v124
	v_mul_f32_e32 v108, v108, v113
	v_mul_f32_e32 v104, v104, v118
	v_mul_f32_e32 v109, v109, v119
	v_mul_f32_e32 v105, v105, v120
	v_mul_f32_e32 v110, v110, v121
	v_mul_f32_e32 v106, v106, v122
	v_mul_f32_e32 v111, v111, v123
	v_mul_f32_e32 v107, v107, v124
	v_mul_f32_e32 v100, v100, v108
	v_mul_f32_e32 v96, v96, v104
	v_mul_f32_e32 v101, v101, v109
	v_mul_f32_e32 v97, v97, v105
	v_mul_f32_e32 v102, v102, v110
	v_mul_f32_e32 v98, v98, v106
	v_mul_f32_e32 v103, v103, v111
	v_mul_f32_e32 v99, v99, v107
	v_add_u32_e32 v100, 0x8000, v100
	v_add_u32_e32 v101, 0x8000, v101
	v_add_u32_e32 v102, 0x8000, v102
	v_add_u32_e32 v103, 0x8000, v103
	v_add_u32_e32 v104, 0x8000, v96
	v_add_u32_e32 v105, 0x8000, v97
	v_add_u32_e32 v106, 0x8000, v98
	v_add_u32_e32 v99, 0x8000, v99
	v_perm_b32 v96, v101, v100, s51
	v_perm_b32 v97, v103, v102, s51
	v_perm_b32 v98, v105, v104, s51
	v_perm_b32 v99, v99, v106, s51
	global_store_dwordx4 v[114:115], v[96:99], off
	s_nop 1
	v_mov_b32_e32 v97, v229
	s_nop 0
	v_or_b32_e32 v96, 48, v144
	v_mad_i64_i32 v[98:99], s[4:5], v112, s49, v[146:147]
	v_lshl_add_u64 v[98:99], v[98:99], 0, v[148:149]
	s_nop 0
	v_fmamk_f32 v97, v97, 0x3a000000, v159
	v_mul_f32_e32 v100, 0x4b800000, v97
	v_cmp_gt_f32_e32 vcc, s50, v97
	s_nop 1
	v_cndmask_b32_e32 v97, v97, v100, vcc
	v_rsq_f32_e32 v102, v97
	v_ashrrev_i32_e32 v97, 31, v96
	v_lshl_add_u64 v[100:101], v[96:97], 2, s[10:11]
	v_mul_f32_e32 v97, 0x45800000, v102
	v_cndmask_b32_e32 v102, v102, v97, vcc
	v_pk_mul_f32 v[94:95], v[94:95], v[102:103] op_sel_hi:[1,0]
	v_pk_mul_f32 v[92:93], v[92:93], v[102:103] op_sel_hi:[1,0]
	v_pk_mul_f32 v[90:91], v[90:91], v[102:103] op_sel_hi:[1,0]
	v_pk_mul_f32 v[88:89], v[88:89], v[102:103] op_sel_hi:[1,0]
	v_pk_mul_f32 v[86:87], v[86:87], v[102:103] op_sel_hi:[1,0]
	v_pk_mul_f32 v[84:85], v[84:85], v[102:103] op_sel_hi:[1,0]
	v_pk_mul_f32 v[82:83], v[82:83], v[102:103] op_sel_hi:[1,0]
	v_pk_mul_f32 v[80:81], v[80:81], v[102:103] op_sel_hi:[1,0]
	v_mul_f32_e32 v97, 0xbfb8aa3b, v92
	v_mul_f32_e32 v102, 0xbfb8aa3b, v88
	v_mul_f32_e32 v103, 0xbfb8aa3b, v93
	v_mul_f32_e32 v104, 0xbfb8aa3b, v89
	v_mul_f32_e32 v105, 0xbfb8aa3b, v94
	v_mul_f32_e32 v106, 0xbfb8aa3b, v90
	v_mul_f32_e32 v107, 0xbfb8aa3b, v95
	v_mul_f32_e32 v108, 0xbfb8aa3b, v91
	v_exp_f32_e32 v97, v97
	v_exp_f32_e32 v102, v102
	v_exp_f32_e32 v103, v103
	v_exp_f32_e32 v104, v104
	v_exp_f32_e32 v105, v105
	v_exp_f32_e32 v106, v106
	v_exp_f32_e32 v107, v107
	v_exp_f32_e32 v108, v108
	v_add_f32_e32 v97, 1.0, v97
	v_add_f32_e32 v102, 1.0, v102
	v_add_f32_e32 v103, 1.0, v103
	v_add_f32_e32 v104, 1.0, v104
	v_add_f32_e32 v105, 1.0, v105
	v_add_f32_e32 v106, 1.0, v106
	v_add_f32_e32 v107, 1.0, v107
	v_add_f32_e32 v108, 1.0, v108
	v_rcp_f32_e32 v97, v97
	v_rcp_f32_e32 v102, v102
	v_rcp_f32_e32 v103, v103
	v_rcp_f32_e32 v104, v104
	v_rcp_f32_e32 v105, v105
	v_rcp_f32_e32 v106, v106
	v_rcp_f32_e32 v107, v107
	v_rcp_f32_e32 v108, v108
	v_mul_f32_e32 v92, v92, v97
	v_mul_f32_e32 v88, v88, v102
	v_mul_f32_e32 v93, v93, v103
	v_mul_f32_e32 v89, v89, v104
	v_mul_f32_e32 v94, v94, v105
	v_mul_f32_e32 v90, v90, v106
	v_mul_f32_e32 v95, v95, v107
	v_mul_f32_e32 v91, v91, v108
	v_mul_f32_e32 v84, v84, v92
	v_mul_f32_e32 v80, v80, v88
	v_mul_f32_e32 v85, v85, v93
	v_mul_f32_e32 v81, v81, v89
	v_mul_f32_e32 v86, v86, v94
	v_mul_f32_e32 v82, v82, v90
	v_mul_f32_e32 v87, v87, v95
	v_mul_f32_e32 v83, v83, v91
	v_add_u32_e32 v84, 0x8000, v84
	v_add_u32_e32 v85, 0x8000, v85
	v_add_u32_e32 v86, 0x8000, v86
	v_add_u32_e32 v87, 0x8000, v87
	v_add_u32_e32 v88, 0x8000, v80
	v_add_u32_e32 v89, 0x8000, v81
	v_add_u32_e32 v90, 0x8000, v82
	v_add_u32_e32 v83, 0x8000, v83
	v_perm_b32 v80, v85, v84, s51
	v_perm_b32 v81, v87, v86, s51
	v_perm_b32 v82, v89, v88, s51
	v_perm_b32 v83, v83, v90, s51
	global_store_dwordx4 v[98:99], v[80:83], off
	s_nop 1
	v_mov_b32_e32 v80, v230
	s_nop 0
	v_fmamk_f32 v80, v80, 0x3a000000, v159
	v_mul_f32_e32 v81, 0x4b800000, v80
	v_cmp_gt_f32_e32 vcc, s50, v80
	s_nop 1
	v_cndmask_b32_e32 v80, v80, v81, vcc
	v_rsq_f32_e32 v82, v80
	v_mad_i64_i32 v[80:81], s[4:5], v96, s49, v[146:147]
	v_lshl_add_u64 v[80:81], v[80:81], 0, v[148:149]
	v_mul_f32_e32 v83, 0x45800000, v82
	v_cndmask_b32_e32 v82, v82, v83, vcc
	v_pk_mul_f32 v[78:79], v[78:79], v[82:83] op_sel_hi:[1,0]
	v_pk_mul_f32 v[76:77], v[76:77], v[82:83] op_sel_hi:[1,0]
	v_pk_mul_f32 v[74:75], v[74:75], v[82:83] op_sel_hi:[1,0]
	v_pk_mul_f32 v[72:73], v[72:73], v[82:83] op_sel_hi:[1,0]
	v_pk_mul_f32 v[70:71], v[70:71], v[82:83] op_sel_hi:[1,0]
	v_pk_mul_f32 v[68:69], v[68:69], v[82:83] op_sel_hi:[1,0]
	v_pk_mul_f32 v[66:67], v[66:67], v[82:83] op_sel_hi:[1,0]
	v_pk_mul_f32 v[64:65], v[64:65], v[82:83] op_sel_hi:[1,0]
	v_mul_f32_e32 v82, 0xbfb8aa3b, v76
	v_mul_f32_e32 v83, 0xbfb8aa3b, v72
	v_mul_f32_e32 v84, 0xbfb8aa3b, v77
	v_mul_f32_e32 v85, 0xbfb8aa3b, v73
	v_mul_f32_e32 v86, 0xbfb8aa3b, v78
	v_mul_f32_e32 v87, 0xbfb8aa3b, v74
	v_mul_f32_e32 v88, 0xbfb8aa3b, v79
	v_mul_f32_e32 v89, 0xbfb8aa3b, v75
	v_exp_f32_e32 v82, v82
	v_exp_f32_e32 v83, v83
	v_exp_f32_e32 v84, v84
	v_exp_f32_e32 v85, v85
	v_exp_f32_e32 v86, v86
	v_exp_f32_e32 v87, v87
	v_exp_f32_e32 v88, v88
	v_exp_f32_e32 v89, v89
	v_add_f32_e32 v82, 1.0, v82
	v_add_f32_e32 v83, 1.0, v83
	v_add_f32_e32 v84, 1.0, v84
	v_add_f32_e32 v85, 1.0, v85
	v_add_f32_e32 v86, 1.0, v86
	v_add_f32_e32 v87, 1.0, v87
	v_add_f32_e32 v88, 1.0, v88
	v_add_f32_e32 v89, 1.0, v89
	v_rcp_f32_e32 v82, v82
	v_rcp_f32_e32 v83, v83
	v_rcp_f32_e32 v84, v84
	v_rcp_f32_e32 v85, v85
	v_rcp_f32_e32 v86, v86
	v_rcp_f32_e32 v87, v87
	v_rcp_f32_e32 v88, v88
	v_rcp_f32_e32 v89, v89
	v_mul_f32_e32 v76, v76, v82
; __device__ __forceinline__ float sigmoid_f(float x) { return __builtin_amdgcn_rcpf(1.f + __expf(-x)); }
; __device__ __forceinline__ float silu_f(float x) { return x * sigmoid_f(x); }
;     __device__ __forceinline__ void operator()(const f32x4 (&acc)[2][2][4][2], const Unit& u, int wr, int wc, int fr, int fq) const {
;         const int row0 = u.pm * BM + wr * 64 + fr, col0 = u.pn * HALF + wc * 32 + 8 * fq;
; #pragma unroll
;         for (int ai = 0; ai < 2; ++ai)
; #pragma unroll
;             for (int m = 0; m < 4; ++m) {
;                 bf16_t* rowp = O + (size_t)(row0 + ai * HALF + m * 16) * ldc + col0;
;                 const float rs = ss ? rsqrtf(ss[row0 + ai * HALF + m * 16] * (1.f / DM) + EPS) : 1.f;
;                 const f32x4 g0 = acc[ai][0][m][0] * rs, g1 = acc[ai][0][m][1] * rs, u0 = acc[ai][1][m][0] * rs, u1 = acc[ai][1][m][1] * rs;
;                 float r[8];
; #pragma unroll
;                 for (int i = 0; i < 4; ++i) {
;                     r[i] = glu ? g0[i] * sigmoid_f(u0[i]) : silu_f(g0[i]) * u0[i];
;                     r[4 + i] = glu ? g1[i] * sigmoid_f(u1[i]) : silu_f(g1[i]) * u1[i];
;                 }
;                 u32x4 w; w.x = pk2(r[0], r[1]); w.y = pk2(r[2], r[3]); w.z = pk2(r[4], r[5]); w.w = pk2(r[6], r[7]);
;                 *(u32x4*)rowp = w;
	v_mul_f32_e32 v72, v72, v83
	v_mul_f32_e32 v77, v77, v84
	v_mul_f32_e32 v73, v73, v85
	v_mul_f32_e32 v78, v78, v86
	v_mul_f32_e32 v74, v74, v87
	v_mul_f32_e32 v79, v79, v88
	v_mul_f32_e32 v75, v75, v89
	v_mul_f32_e32 v68, v68, v76
	v_mul_f32_e32 v64, v64, v72
	v_mul_f32_e32 v69, v69, v77
	v_mul_f32_e32 v65, v65, v73
	v_mul_f32_e32 v70, v70, v78
	v_mul_f32_e32 v66, v66, v74
	v_mul_f32_e32 v71, v71, v79
	v_mul_f32_e32 v67, v67, v75
	v_add_u32_e32 v68, 0x8000, v68
	v_add_u32_e32 v69, 0x8000, v69
	v_add_u32_e32 v70, 0x8000, v70
	v_add_u32_e32 v71, 0x8000, v71
	v_add_u32_e32 v72, 0x8000, v64
	v_add_u32_e32 v73, 0x8000, v65
	v_add_u32_e32 v74, 0x8000, v66
	v_add_u32_e32 v67, 0x8000, v67
	v_perm_b32 v64, v69, v68, s51
	v_perm_b32 v65, v71, v70, s51
	v_perm_b32 v66, v73, v72, s51
	v_perm_b32 v67, v67, v74, s51
	global_store_dwordx4 v[80:81], v[64:67], off
	s_nop 1
	v_mov_b32_e32 v64, v231
	s_nop 0
	v_add_u32_e32 v65, 0x80, v144
	s_nop 0
	v_fmamk_f32 v64, v64, 0x3a000000, v159
	v_mul_f32_e32 v66, 0x4b800000, v64
	v_cmp_gt_f32_e32 vcc, s50, v64
	s_nop 1
	v_cndmask_b32_e32 v64, v64, v66, vcc
	v_rsq_f32_e32 v66, v64
	v_mad_i64_i32 v[64:65], s[4:5], v65, s49, v[146:147]
	v_lshl_add_u64 v[64:65], v[64:65], 0, v[148:149]
	v_mul_f32_e32 v67, 0x45800000, v66
	v_cndmask_b32_e32 v66, v66, v67, vcc
	v_pk_mul_f32 v[62:63], v[62:63], v[66:67] op_sel_hi:[1,0]
	v_pk_mul_f32 v[60:61], v[60:61], v[66:67] op_sel_hi:[1,0]
	v_pk_mul_f32 v[58:59], v[58:59], v[66:67] op_sel_hi:[1,0]
	v_pk_mul_f32 v[56:57], v[56:57], v[66:67] op_sel_hi:[1,0]
	v_pk_mul_f32 v[54:55], v[54:55], v[66:67] op_sel_hi:[1,0]
	v_pk_mul_f32 v[52:53], v[52:53], v[66:67] op_sel_hi:[1,0]
	v_pk_mul_f32 v[50:51], v[50:51], v[66:67] op_sel_hi:[1,0]
	v_pk_mul_f32 v[48:49], v[48:49], v[66:67] op_sel_hi:[1,0]
	v_mul_f32_e32 v66, 0xbfb8aa3b, v60
	v_mul_f32_e32 v67, 0xbfb8aa3b, v56
	v_mul_f32_e32 v68, 0xbfb8aa3b, v61
	v_mul_f32_e32 v69, 0xbfb8aa3b, v57
	v_mul_f32_e32 v70, 0xbfb8aa3b, v62
	v_mul_f32_e32 v71, 0xbfb8aa3b, v58
	v_mul_f32_e32 v72, 0xbfb8aa3b, v63
	v_mul_f32_e32 v73, 0xbfb8aa3b, v59
	v_exp_f32_e32 v66, v66
	v_exp_f32_e32 v67, v67
	v_exp_f32_e32 v68, v68
	v_exp_f32_e32 v69, v69
	v_exp_f32_e32 v70, v70
	v_exp_f32_e32 v71, v71
	v_exp_f32_e32 v72, v72
	v_exp_f32_e32 v73, v73
	v_add_f32_e32 v66, 1.0, v66
	v_add_f32_e32 v67, 1.0, v67
	v_add_f32_e32 v68, 1.0, v68
	v_add_f32_e32 v69, 1.0, v69
	v_add_f32_e32 v70, 1.0, v70
	v_add_f32_e32 v71, 1.0, v71
	v_add_f32_e32 v72, 1.0, v72
	v_add_f32_e32 v73, 1.0, v73
	v_rcp_f32_e32 v66, v66
	v_rcp_f32_e32 v67, v67
	v_rcp_f32_e32 v68, v68
	v_rcp_f32_e32 v69, v69
	v_rcp_f32_e32 v70, v70
	v_rcp_f32_e32 v71, v71
	v_rcp_f32_e32 v72, v72
	v_rcp_f32_e32 v73, v73
	v_mul_f32_e32 v60, v60, v66
	v_mul_f32_e32 v56, v56, v67
	v_mul_f32_e32 v61, v61, v68
	v_mul_f32_e32 v57, v57, v69
	v_mul_f32_e32 v62, v62, v70
	v_mul_f32_e32 v58, v58, v71
	v_mul_f32_e32 v63, v63, v72
	v_mul_f32_e32 v59, v59, v73
	v_mul_f32_e32 v52, v52, v60
	v_mul_f32_e32 v48, v48, v56
	v_mul_f32_e32 v53, v53, v61
	v_mul_f32_e32 v49, v49, v57
	v_mul_f32_e32 v54, v54, v62
	v_mul_f32_e32 v50, v50, v58
	v_mul_f32_e32 v55, v55, v63
	v_mul_f32_e32 v51, v51, v59
	v_add_u32_e32 v52, 0x8000, v52
	v_add_u32_e32 v53, 0x8000, v53
	v_add_u32_e32 v54, 0x8000, v54
	v_add_u32_e32 v55, 0x8000, v55
	v_add_u32_e32 v56, 0x8000, v48
	v_add_u32_e32 v57, 0x8000, v49
	v_add_u32_e32 v58, 0x8000, v50
	v_add_u32_e32 v51, 0x8000, v51
	v_perm_b32 v48, v53, v52, s51
	v_perm_b32 v49, v55, v54, s51
	v_perm_b32 v50, v57, v56, s51
	v_perm_b32 v51, v51, v58, s51
	global_store_dwordx4 v[64:65], v[48:51], off
	s_nop 1
	v_mov_b32_e32 v48, v232
	s_nop 0
	v_add_u32_e32 v49, 0x90, v144
	s_nop 0
	v_fmamk_f32 v48, v48, 0x3a000000, v159
	v_mul_f32_e32 v50, 0x4b800000, v48
	v_cmp_gt_f32_e32 vcc, s50, v48
	s_nop 1
	v_cndmask_b32_e32 v48, v48, v50, vcc
	v_rsq_f32_e32 v50, v48
	v_mad_i64_i32 v[48:49], s[4:5], v49, s49, v[146:147]
	v_lshl_add_u64 v[48:49], v[48:49], 0, v[148:149]
	v_mul_f32_e32 v51, 0x45800000, v50
	v_cndmask_b32_e32 v50, v50, v51, vcc
	v_pk_mul_f32 v[46:47], v[46:47], v[50:51] op_sel_hi:[1,0]
	v_pk_mul_f32 v[44:45], v[44:45], v[50:51] op_sel_hi:[1,0]
	v_pk_mul_f32 v[42:43], v[42:43], v[50:51] op_sel_hi:[1,0]
	v_pk_mul_f32 v[40:41], v[40:41], v[50:51] op_sel_hi:[1,0]
	v_pk_mul_f32 v[38:39], v[38:39], v[50:51] op_sel_hi:[1,0]
	v_pk_mul_f32 v[36:37], v[36:37], v[50:51] op_sel_hi:[1,0]
	v_pk_mul_f32 v[34:35], v[34:35], v[50:51] op_sel_hi:[1,0]
	v_pk_mul_f32 v[32:33], v[32:33], v[50:51] op_sel_hi:[1,0]
	v_mul_f32_e32 v50, 0xbfb8aa3b, v44
	v_mul_f32_e32 v51, 0xbfb8aa3b, v40
	v_mul_f32_e32 v52, 0xbfb8aa3b, v45
	v_mul_f32_e32 v53, 0xbfb8aa3b, v41
	v_mul_f32_e32 v54, 0xbfb8aa3b, v46
	v_mul_f32_e32 v55, 0xbfb8aa3b, v42
	v_mul_f32_e32 v56, 0xbfb8aa3b, v47
	v_mul_f32_e32 v57, 0xbfb8aa3b, v43
	v_exp_f32_e32 v50, v50
	v_exp_f32_e32 v51, v51
	v_exp_f32_e32 v52, v52
	v_exp_f32_e32 v53, v53
	v_exp_f32_e32 v54, v54
	v_exp_f32_e32 v55, v55
	v_exp_f32_e32 v56, v56
	v_exp_f32_e32 v57, v57
	v_add_f32_e32 v50, 1.0, v50
	v_add_f32_e32 v51, 1.0, v51
	v_add_f32_e32 v52, 1.0, v52
	v_add_f32_e32 v53, 1.0, v53
	v_add_f32_e32 v54, 1.0, v54
	v_add_f32_e32 v55, 1.0, v55
	v_add_f32_e32 v56, 1.0, v56
	v_add_f32_e32 v57, 1.0, v57
	v_rcp_f32_e32 v50, v50
	v_rcp_f32_e32 v51, v51
	v_rcp_f32_e32 v52, v52
	v_rcp_f32_e32 v53, v53
	v_rcp_f32_e32 v54, v54
	v_rcp_f32_e32 v55, v55
	v_rcp_f32_e32 v56, v56
	v_rcp_f32_e32 v57, v57
	v_mul_f32_e32 v44, v44, v50
	v_mul_f32_e32 v40, v40, v51
	v_mul_f32_e32 v45, v45, v52
	v_mul_f32_e32 v41, v41, v53
	v_mul_f32_e32 v46, v46, v54
	v_mul_f32_e32 v42, v42, v55
	v_mul_f32_e32 v47, v47, v56
	v_mul_f32_e32 v43, v43, v57
	v_mul_f32_e32 v36, v36, v44
; __device__ __forceinline__ float sigmoid_f(float x) { return __builtin_amdgcn_rcpf(1.f + __expf(-x)); }
; __device__ __forceinline__ float silu_f(float x) { return x * sigmoid_f(x); }
;     __device__ __forceinline__ void operator()(const f32x4 (&acc)[2][2][4][2], const Unit& u, int wr, int wc, int fr, int fq) const {
;         const int row0 = u.pm * BM + wr * 64 + fr, col0 = u.pn * HALF + wc * 32 + 8 * fq;
; #pragma unroll
;         for (int ai = 0; ai < 2; ++ai)
; #pragma unroll
;             for (int m = 0; m < 4; ++m) {
;                 bf16_t* rowp = O + (size_t)(row0 + ai * HALF + m * 16) * ldc + col0;
;                 const float rs = ss ? rsqrtf(ss[row0 + ai * HALF + m * 16] * (1.f / DM) + EPS) : 1.f;
;                 const f32x4 g0 = acc[ai][0][m][0] * rs, g1 = acc[ai][0][m][1] * rs, u0 = acc[ai][1][m][0] * rs, u1 = acc[ai][1][m][1] * rs;
;                 float r[8];
; #pragma unroll
;                 for (int i = 0; i < 4; ++i) {
;                     r[i] = glu ? g0[i] * sigmoid_f(u0[i]) : silu_f(g0[i]) * u0[i];
;                     r[4 + i] = glu ? g1[i] * sigmoid_f(u1[i]) : silu_f(g1[i]) * u1[i];
;                 }
;                 u32x4 w; w.x = pk2(r[0], r[1]); w.y = pk2(r[2], r[3]); w.z = pk2(r[4], r[5]); w.w = pk2(r[6], r[7]);
;                 *(u32x4*)rowp = w;
;             }
	v_mul_f32_e32 v32, v32, v40
	v_mul_f32_e32 v37, v37, v45
	v_mul_f32_e32 v33, v33, v41
	v_mul_f32_e32 v38, v38, v46
	v_mul_f32_e32 v34, v34, v42
	v_mul_f32_e32 v39, v39, v47
	v_mul_f32_e32 v35, v35, v43
	v_add_u32_e32 v36, 0x8000, v36
	v_add_u32_e32 v37, 0x8000, v37
	v_add_u32_e32 v38, 0x8000, v38
	v_add_u32_e32 v39, 0x8000, v39
	v_add_u32_e32 v40, 0x8000, v32
	v_add_u32_e32 v41, 0x8000, v33
	v_add_u32_e32 v42, 0x8000, v34
	v_add_u32_e32 v35, 0x8000, v35
	v_perm_b32 v32, v37, v36, s51
	v_perm_b32 v33, v39, v38, s51
	v_perm_b32 v34, v41, v40, s51
	v_perm_b32 v35, v35, v42, s51
	global_store_dwordx4 v[48:49], v[32:35], off
	s_nop 1
	v_mov_b32_e32 v32, v233
	s_nop 0
	v_add_u32_e32 v33, 0xa0, v144
	s_nop 0
	v_fmamk_f32 v32, v32, 0x3a000000, v159
	v_mul_f32_e32 v34, 0x4b800000, v32
	v_cmp_gt_f32_e32 vcc, s50, v32
	s_nop 1
	v_cndmask_b32_e32 v32, v32, v34, vcc
	v_rsq_f32_e32 v34, v32
	v_mad_i64_i32 v[32:33], s[4:5], v33, s49, v[146:147]
	v_lshl_add_u64 v[32:33], v[32:33], 0, v[148:149]
	v_mul_f32_e32 v35, 0x45800000, v34
	v_cndmask_b32_e32 v34, v34, v35, vcc
	v_pk_mul_f32 v[30:31], v[30:31], v[34:35] op_sel_hi:[1,0]
	v_pk_mul_f32 v[28:29], v[28:29], v[34:35] op_sel_hi:[1,0]
	v_pk_mul_f32 v[26:27], v[26:27], v[34:35] op_sel_hi:[1,0]
	v_pk_mul_f32 v[24:25], v[24:25], v[34:35] op_sel_hi:[1,0]
	v_pk_mul_f32 v[22:23], v[22:23], v[34:35] op_sel_hi:[1,0]
	v_pk_mul_f32 v[20:21], v[20:21], v[34:35] op_sel_hi:[1,0]
	v_pk_mul_f32 v[18:19], v[18:19], v[34:35] op_sel_hi:[1,0]
	v_pk_mul_f32 v[16:17], v[16:17], v[34:35] op_sel_hi:[1,0]
	v_mul_f32_e32 v34, 0xbfb8aa3b, v28
	v_mul_f32_e32 v35, 0xbfb8aa3b, v24
	v_mul_f32_e32 v36, 0xbfb8aa3b, v29
	v_mul_f32_e32 v37, 0xbfb8aa3b, v25
	v_mul_f32_e32 v38, 0xbfb8aa3b, v30
	v_mul_f32_e32 v39, 0xbfb8aa3b, v26
	v_mul_f32_e32 v40, 0xbfb8aa3b, v31
	v_mul_f32_e32 v41, 0xbfb8aa3b, v27
	v_exp_f32_e32 v34, v34
	v_exp_f32_e32 v35, v35
	v_exp_f32_e32 v36, v36
	v_exp_f32_e32 v37, v37
	v_exp_f32_e32 v38, v38
	v_exp_f32_e32 v39, v39
	v_exp_f32_e32 v40, v40
	v_exp_f32_e32 v41, v41
	v_add_f32_e32 v34, 1.0, v34
	v_add_f32_e32 v35, 1.0, v35
	v_add_f32_e32 v36, 1.0, v36
	v_add_f32_e32 v37, 1.0, v37
	v_add_f32_e32 v38, 1.0, v38
	v_add_f32_e32 v39, 1.0, v39
	v_add_f32_e32 v40, 1.0, v40
	v_add_f32_e32 v41, 1.0, v41
	v_rcp_f32_e32 v34, v34
	v_rcp_f32_e32 v35, v35
	v_rcp_f32_e32 v36, v36
	v_rcp_f32_e32 v37, v37
	v_rcp_f32_e32 v38, v38
	v_rcp_f32_e32 v39, v39
	v_rcp_f32_e32 v40, v40
	v_rcp_f32_e32 v41, v41
	v_mul_f32_e32 v28, v28, v34
	v_mul_f32_e32 v24, v24, v35
	v_mul_f32_e32 v29, v29, v36
	v_mul_f32_e32 v25, v25, v37
	v_mul_f32_e32 v30, v30, v38
	v_mul_f32_e32 v26, v26, v39
	v_mul_f32_e32 v31, v31, v40
	v_mul_f32_e32 v27, v27, v41
	v_mul_f32_e32 v20, v20, v28
	v_mul_f32_e32 v16, v16, v24
	v_mul_f32_e32 v21, v21, v29
	v_mul_f32_e32 v17, v17, v25
	v_mul_f32_e32 v22, v22, v30
	v_mul_f32_e32 v18, v18, v26
	v_mul_f32_e32 v23, v23, v31
	v_mul_f32_e32 v19, v19, v27
	v_add_u32_e32 v20, 0x8000, v20
	v_add_u32_e32 v21, 0x8000, v21
	v_add_u32_e32 v22, 0x8000, v22
	v_add_u32_e32 v23, 0x8000, v23
	v_add_u32_e32 v24, 0x8000, v16
	v_add_u32_e32 v25, 0x8000, v17
	v_add_u32_e32 v26, 0x8000, v18
	v_add_u32_e32 v19, 0x8000, v19
	v_perm_b32 v16, v21, v20, s51
	v_perm_b32 v17, v23, v22, s51
	v_perm_b32 v18, v25, v24, s51
	v_perm_b32 v19, v19, v26, s51
	global_store_dwordx4 v[32:33], v[16:19], off
	s_nop 1
	v_mov_b32_e32 v16, v234
	s_andn2_b64 vcc, exec, s[0:1]
	v_add_u32_e32 v17, 0xb0, v144
	s_mov_b64 s[0:1], -1
	s_nop 0
	v_fmamk_f32 v16, v16, 0x3a000000, v159
	v_mul_f32_e32 v18, 0x4b800000, v16
	v_cmp_gt_f32_e64 s[4:5], s50, v16
	s_nop 1
	v_cndmask_b32_e64 v16, v16, v18, s[4:5]
	v_rsq_f32_e32 v18, v16
	v_mad_i64_i32 v[16:17], s[24:25], v17, s49, v[146:147]
	v_lshl_add_u64 v[16:17], v[16:17], 0, v[148:149]
	v_mul_f32_e32 v19, 0x45800000, v18
	v_cndmask_b32_e64 v18, v18, v19, s[4:5]
	v_pk_mul_f32 v[14:15], v[14:15], v[18:19] op_sel_hi:[1,0]
	v_pk_mul_f32 v[12:13], v[12:13], v[18:19] op_sel_hi:[1,0]
	v_pk_mul_f32 v[10:11], v[10:11], v[18:19] op_sel_hi:[1,0]
	v_pk_mul_f32 v[8:9], v[8:9], v[18:19] op_sel_hi:[1,0]
	v_pk_mul_f32 v[6:7], v[6:7], v[18:19] op_sel_hi:[1,0]
	v_pk_mul_f32 v[4:5], v[4:5], v[18:19] op_sel_hi:[1,0]
	v_pk_mul_f32 v[2:3], v[2:3], v[18:19] op_sel_hi:[1,0]
	v_pk_mul_f32 v[0:1], v[0:1], v[18:19] op_sel_hi:[1,0]
	v_mul_f32_e32 v18, 0xbfb8aa3b, v12
	v_mul_f32_e32 v19, 0xbfb8aa3b, v8
	v_mul_f32_e32 v20, 0xbfb8aa3b, v13
	v_mul_f32_e32 v21, 0xbfb8aa3b, v9
	v_mul_f32_e32 v22, 0xbfb8aa3b, v14
	v_mul_f32_e32 v23, 0xbfb8aa3b, v10
	v_mul_f32_e32 v24, 0xbfb8aa3b, v15
	v_mul_f32_e32 v25, 0xbfb8aa3b, v11
	v_exp_f32_e32 v18, v18
	v_exp_f32_e32 v19, v19
	v_exp_f32_e32 v20, v20
	v_exp_f32_e32 v21, v21
	v_exp_f32_e32 v22, v22
	v_exp_f32_e32 v23, v23
	v_exp_f32_e32 v24, v24
	v_exp_f32_e32 v25, v25
	v_add_f32_e32 v18, 1.0, v18
	v_add_f32_e32 v19, 1.0, v19
	v_add_f32_e32 v20, 1.0, v20
	v_add_f32_e32 v21, 1.0, v21
	v_add_f32_e32 v22, 1.0, v22
	v_add_f32_e32 v23, 1.0, v23
	v_add_f32_e32 v24, 1.0, v24
	v_add_f32_e32 v25, 1.0, v25
	v_rcp_f32_e32 v18, v18
	v_rcp_f32_e32 v19, v19
	v_rcp_f32_e32 v20, v20
	v_rcp_f32_e32 v21, v21
	v_rcp_f32_e32 v22, v22
	v_rcp_f32_e32 v23, v23
	v_rcp_f32_e32 v24, v24
	v_rcp_f32_e32 v25, v25
	v_mul_f32_e32 v12, v12, v18
	v_mul_f32_e32 v8, v8, v19
	v_mul_f32_e32 v13, v13, v20
	v_mul_f32_e32 v9, v9, v21
	v_mul_f32_e32 v14, v14, v22
	v_mul_f32_e32 v10, v10, v23
	v_mul_f32_e32 v15, v15, v24
	v_mul_f32_e32 v11, v11, v25
	v_mul_f32_e32 v4, v4, v12
	v_mul_f32_e32 v0, v0, v8
	v_mul_f32_e32 v5, v5, v13
	v_mul_f32_e32 v1, v1, v9
	v_mul_f32_e32 v6, v6, v14
	v_mul_f32_e32 v2, v2, v10
	v_mul_f32_e32 v7, v7, v15
	v_mul_f32_e32 v3, v3, v11
	v_add_u32_e32 v4, 0x8000, v4
	v_add_u32_e32 v5, 0x8000, v5
	v_add_u32_e32 v6, 0x8000, v6
	v_add_u32_e32 v7, 0x8000, v7
	v_add_u32_e32 v8, 0x8000, v0
	v_add_u32_e32 v9, 0x8000, v1
	v_add_u32_e32 v10, 0x8000, v2
	v_add_u32_e32 v3, 0x8000, v3
	v_perm_b32 v0, v5, v4, s51
	v_perm_b32 v1, v7, v6, s51
	v_perm_b32 v2, v9, v8, s51
	v_perm_b32 v3, v3, v10, s51
	global_store_dwordx4 v[16:17], v[0:3], off
	s_cbranch_vccnz .LBB0_1289
	s_andn2_b64 vcc, exec, s[6:7]
	s_cbranch_vccnz .LBB0_1288
	s_barrier
	s_branch .LBB0_1288
